# non-temporal hint also on the LDS-DMA operand loads of the mix-phase GEMM units
# baseline (speedup 1.0000x reference)
.LBB0_1075:
	s_cmp_lg_u64 s[0:1], 0
	s_cselect_b64 s[18:19], -1, 0
	v_cndmask_b32_e64 v0, 0, 1, s[18:19]
	v_bfe_u32 v1, v144, 3, 3
	v_readfirstlane_b32 s17, v0
	v_ashrrev_i32_e32 v0, 6, v144
	v_lshl_or_b32 v5, v0, 3, v1
	v_lshrrev_b32_e32 v6, 1, v5
	v_ashrrev_i32_e32 v8, 31, v0
	v_lshlrev_b32_e32 v163, 10, v0
	v_xor_b32_e32 v2, v6, v144
	v_mul_lo_u32 v3, s80, v8
	v_mul_lo_u32 v9, s81, v5
	v_mad_u64_u32 v[0:1], s[18:19], s80, v5, 0
	s_and_b64 s[18:19], s[72:73], exec
	v_add_u32_e32 v7, 32, v163
	v_add3_u32 v1, v1, v3, v9
	v_lshlrev_b32_e32 v2, 4, v2
	v_lshl_add_u64 v[0:1], v[0:1], 1, s[78:79]
	v_and_b32_e32 v2, 0x70, v2
	v_mov_b32_e32 v3, v4
	v_readfirstlane_b32 s18, v7
	v_lshl_add_u64 v[0:1], v[0:1], 0, v[2:3]
	s_mov_b32 m0, s18
	v_mul_lo_u32 v9, s76, v8
	global_load_lds_dwordx4 v[0:1], off nt
	v_mul_lo_u32 v10, s77, v5
	v_mad_u64_u32 v[0:1], s[18:19], s76, v5, 0
	v_add3_u32 v1, v1, v9, v10
	v_add_u32_e32 v9, 0x8000, v7
	v_lshl_add_u64 v[0:1], v[0:1], 1, s[4:5]
	v_readfirstlane_b32 s18, v9
	v_add_u32_e32 v9, 64, v5
	v_lshl_add_u64 v[0:1], v[0:1], 0, v[2:3]
	s_mov_b32 m0, s18
	v_ashrrev_i32_e32 v11, 31, v9
	global_load_lds_dwordx4 v[0:1], off nt
	v_mul_lo_u32 v12, s80, v11
	v_mul_lo_u32 v13, s81, v9
	v_mad_u64_u32 v[0:1], s[18:19], s80, v9, 0
	v_add_u32_e32 v10, 0x2000, v7
	v_add3_u32 v1, v1, v12, v13
	v_lshl_add_u64 v[0:1], v[0:1], 1, s[78:79]
	v_readfirstlane_b32 s18, v10
	v_lshl_add_u64 v[0:1], v[0:1], 0, v[2:3]
	s_mov_b32 m0, s18
	v_mul_lo_u32 v10, s76, v11
	global_load_lds_dwordx4 v[0:1], off nt
	v_mul_lo_u32 v12, s77, v9
	v_mad_u64_u32 v[0:1], s[18:19], s76, v9, 0
	v_add3_u32 v1, v1, v10, v12
	v_add_u32_e32 v10, 0xa000, v7
	v_lshl_add_u64 v[0:1], v[0:1], 1, s[4:5]
	v_readfirstlane_b32 s18, v10
	v_add_u32_e32 v10, 0x80, v5
	v_lshl_add_u64 v[0:1], v[0:1], 0, v[2:3]
	s_mov_b32 m0, s18
	v_ashrrev_i32_e32 v13, 31, v10
	global_load_lds_dwordx4 v[0:1], off nt
	v_mul_lo_u32 v14, s80, v13
	v_mul_lo_u32 v15, s81, v10
	v_mad_u64_u32 v[0:1], s[18:19], s80, v10, 0
	v_add_u32_e32 v12, 0x4000, v7
	v_add3_u32 v1, v1, v14, v15
	v_lshl_add_u64 v[0:1], v[0:1], 1, s[78:79]
	v_readfirstlane_b32 s18, v12
	v_lshl_add_u64 v[0:1], v[0:1], 0, v[2:3]
	s_mov_b32 m0, s18
	v_mul_lo_u32 v12, s76, v13
	global_load_lds_dwordx4 v[0:1], off nt
	v_mul_lo_u32 v14, s77, v10
	v_mad_u64_u32 v[0:1], s[18:19], s76, v10, 0
	v_add3_u32 v1, v1, v12, v14
	v_add_u32_e32 v12, 0xc000, v7
	v_lshl_add_u64 v[0:1], v[0:1], 1, s[4:5]
	v_readfirstlane_b32 s18, v12
	v_add_u32_e32 v12, 0xc0, v5
	v_lshl_add_u64 v[0:1], v[0:1], 0, v[2:3]
	s_mov_b32 m0, s18
	v_ashrrev_i32_e32 v15, 31, v12
	global_load_lds_dwordx4 v[0:1], off nt
	v_mul_lo_u32 v16, s80, v15
	v_mul_lo_u32 v17, s81, v12
	v_mad_u64_u32 v[0:1], s[18:19], s80, v12, 0
	v_add_u32_e32 v14, 0x6000, v7
	v_add3_u32 v1, v1, v16, v17
	v_lshl_add_u64 v[0:1], v[0:1], 1, s[78:79]
	v_readfirstlane_b32 s18, v14
	v_lshl_add_u64 v[0:1], v[0:1], 0, v[2:3]
	s_mov_b32 m0, s18
	v_mul_lo_u32 v14, s76, v15
	global_load_lds_dwordx4 v[0:1], off nt
	v_mul_lo_u32 v16, s77, v12
	v_mad_u64_u32 v[0:1], s[18:19], s76, v12, 0
	v_add3_u32 v1, v1, v14, v16
	v_lshl_add_u64 v[0:1], v[0:1], 1, s[4:5]
	v_lshl_add_u64 v[0:1], v[0:1], 0, v[2:3]
	v_add_u32_e32 v2, 0xe000, v7
	v_bfe_u32 v3, v144, 1, 3
	v_readfirstlane_b32 s18, v2
	s_mov_b32 m0, s18
	s_cselect_b32 s17, 2, s17
	global_load_lds_dwordx4 v[0:1], off nt
	v_lshrrev_b32_e32 v0, 5, v144
	v_bitop3_b32 v0, v0, v3, 1 bitop3:0x6c
	s_cmp_eq_u32 s17, 0
	v_bfe_u32 v1, v144, 5, 1
	v_lshlrev_b32_e32 v166, 4, v0
	v_lshlrev_b32_e32 v0, 7, v144
	s_cselect_b64 s[72:73], -1, 0
	s_cmp_lg_u32 s17, 0
	v_and_b32_e32 v159, 0x6f80, v0
	v_bitop3_b32 v0, v1, v3, 2 bitop3:0x36
	s_mov_b32 s23, s69
	s_cselect_b64 s[74:75], -1, 0
	v_lshlrev_b32_e32 v165, 4, v0
	v_bitop3_b32 v0, v1, v3, 4 bitop3:0x36
	s_lshl_b64 s[50:51], s[22:23], 7
	v_lshlrev_b32_e32 v164, 4, v0
	v_bitop3_b32 v0, v1, v3, 6 bitop3:0x36
	s_add_u32 s19, s50, 0x80
	v_and_b32_e32 v161, 31, v144
	v_lshrrev_b32_e32 v2, 1, v144
	s_mov_b32 s18, 0x1ffff80
	v_lshlrev_b32_e32 v162, 4, v0
	s_add_u32 s50, s78, 0x80
	v_bitop3_b32 v0, v6, 7, v144 bitop3:0x48
	v_and_or_b32 v2, v2, s18, v161
	s_ff1_i32_b32 s18, s17
	s_addc_u32 s51, s79, 0
	s_lshl_b32 s17, s80, 1
	v_lshlrev_b32_e32 v0, 4, v0
	v_mov_b32_e32 v1, v4
	v_lshlrev_b32_e32 v158, 7, v2
	v_mad_u64_u32 v[2:3], s[56:57], s17, v5, v[0:1]
	s_lshr_b64 s[56:57], s[80:81], 31
	s_nop 0
	v_mul_lo_u32 v6, s56, v5
	v_mul_lo_u32 v7, s17, v8
	v_add3_u32 v3, v6, v3, v7
	v_lshl_add_u64 v[134:135], s[50:51], 0, v[2:3]
	v_mad_u64_u32 v[2:3], s[60:61], s17, v9, v[0:1]
	v_mul_lo_u32 v6, s56, v9
	v_mul_lo_u32 v7, s17, v11
	v_add3_u32 v3, v6, v3, v7
	v_lshl_add_u64 v[136:137], s[50:51], 0, v[2:3]
	v_mad_u64_u32 v[2:3], s[60:61], s17, v10, v[0:1]
	v_mul_lo_u32 v6, s56, v10
	v_mul_lo_u32 v7, s17, v13
	v_add3_u32 v3, v6, v3, v7
	v_lshl_add_u64 v[146:147], s[50:51], 0, v[2:3]
	v_mad_u64_u32 v[2:3], s[60:61], s17, v12, v[0:1]
	v_mul_lo_u32 v6, s56, v12
	v_mul_lo_u32 v7, s17, v15
	s_add_u32 s4, s4, 0x80
	v_add3_u32 v3, v6, v3, v7
	s_addc_u32 s5, s5, 0
	s_lshl_b32 s17, s76, 1
	v_lshl_add_u64 v[148:149], s[50:51], 0, v[2:3]
	v_mad_u64_u32 v[2:3], s[50:51], s17, v5, v[0:1]
	s_lshr_b64 s[50:51], s[76:77], 31
	s_nop 0
	v_mul_lo_u32 v5, s50, v5
	v_mul_lo_u32 v6, s17, v8
	v_add3_u32 v3, v5, v3, v6
	v_lshl_add_u64 v[150:151], s[4:5], 0, v[2:3]
	v_mad_u64_u32 v[2:3], s[56:57], s17, v9, v[0:1]
	v_mul_lo_u32 v5, s50, v9
	v_mul_lo_u32 v6, s17, v11
	v_add3_u32 v3, v5, v3, v6
	v_lshl_add_u64 v[152:153], s[4:5], 0, v[2:3]
	v_mad_u64_u32 v[2:3], s[56:57], s17, v10, v[0:1]
	v_mul_lo_u32 v5, s50, v10
	v_mul_lo_u32 v6, s17, v13
	v_add3_u32 v3, v5, v3, v6
	v_lshl_add_u64 v[154:155], s[4:5], 0, v[2:3]
	v_mad_u64_u32 v[0:1], s[56:57], s17, v12, v[0:1]
	v_mul_lo_u32 v2, s50, v12
	v_mul_lo_u32 v3, s17, v15
	v_add3_u32 v1, v2, v1, v3
	v_mov_b32_e32 v14, v4
	v_mov_b32_e32 v15, v4
	s_waitcnt vmcnt(0)
	v_lshl_add_u64 v[156:157], s[4:5], 0, v[0:1]
	v_mov_b32_e32 v0, v4
	v_mov_b32_e32 v1, v4
	v_mov_b32_e32 v2, v4
	v_mov_b32_e32 v3, v4
	v_mov_b32_e32 v5, v4
	v_mov_b32_e32 v6, v4
	v_mov_b32_e32 v7, v4
	v_mov_b32_e32 v8, v4
	v_mov_b32_e32 v9, v4
	v_mov_b32_e32 v10, v4
	v_mov_b32_e32 v11, v4
	v_mov_b32_e32 v12, v4
	v_mov_b32_e32 v13, v4
	v_mov_b64_e32 v[116:117], v[14:15]
	v_mov_b64_e32 v[132:133], v[14:15]
	v_mov_b64_e32 v[100:101], v[14:15]
	v_mov_b64_e32 v[84:85], v[14:15]
	v_mov_b64_e32 v[68:69], v[14:15]
	v_mov_b64_e32 v[52:53], v[14:15]
	v_mov_b64_e32 v[36:37], v[14:15]
	v_mov_b64_e32 v[114:115], v[12:13]
	v_mov_b64_e32 v[112:113], v[10:11]
	v_mov_b64_e32 v[110:111], v[8:9]
	v_mov_b64_e32 v[108:109], v[6:7]
	v_mov_b64_e32 v[106:107], v[4:5]
	v_mov_b64_e32 v[104:105], v[2:3]
	v_mov_b64_e32 v[102:103], v[0:1]
	v_mov_b64_e32 v[130:131], v[12:13]
	v_mov_b64_e32 v[128:129], v[10:11]
	v_mov_b64_e32 v[126:127], v[8:9]
	v_mov_b64_e32 v[124:125], v[6:7]
	v_mov_b64_e32 v[122:123], v[4:5]
	v_mov_b64_e32 v[120:121], v[2:3]
	v_mov_b64_e32 v[118:119], v[0:1]
	v_mov_b64_e32 v[98:99], v[12:13]
	v_mov_b64_e32 v[96:97], v[10:11]
	v_mov_b64_e32 v[94:95], v[8:9]
	v_mov_b64_e32 v[92:93], v[6:7]
	v_mov_b64_e32 v[90:91], v[4:5]
	v_mov_b64_e32 v[88:89], v[2:3]
	v_mov_b64_e32 v[86:87], v[0:1]
	v_mov_b64_e32 v[82:83], v[12:13]
	v_mov_b64_e32 v[80:81], v[10:11]
	v_mov_b64_e32 v[78:79], v[8:9]
	v_mov_b64_e32 v[76:77], v[6:7]
	v_mov_b64_e32 v[74:75], v[4:5]
	v_mov_b64_e32 v[72:73], v[2:3]
	v_mov_b64_e32 v[70:71], v[0:1]
	v_mov_b64_e32 v[66:67], v[12:13]
	v_mov_b64_e32 v[64:65], v[10:11]
	v_mov_b64_e32 v[62:63], v[8:9]
	v_mov_b64_e32 v[60:61], v[6:7]
	v_mov_b64_e32 v[58:59], v[4:5]
	v_mov_b64_e32 v[56:57], v[2:3]
	v_mov_b64_e32 v[54:55], v[0:1]
	v_mov_b64_e32 v[50:51], v[12:13]
	v_mov_b64_e32 v[48:49], v[10:11]
	v_mov_b64_e32 v[46:47], v[8:9]
	v_mov_b64_e32 v[44:45], v[6:7]
	v_mov_b64_e32 v[42:43], v[4:5]
	v_mov_b64_e32 v[40:41], v[2:3]
	v_mov_b64_e32 v[38:39], v[0:1]
	v_mov_b64_e32 v[34:35], v[12:13]
	v_mov_b64_e32 v[32:33], v[10:11]
	v_mov_b64_e32 v[30:31], v[8:9]
	v_mov_b64_e32 v[28:29], v[6:7]
	v_mov_b64_e32 v[26:27], v[4:5]
	v_mov_b64_e32 v[24:25], v[2:3]
	v_mov_b64_e32 v[22:23], v[0:1]
	v_mov_b64_e32 v[20:21], v[14:15]
	s_mov_b64 s[70:71], 0
	v_lshrrev_b32_e32 v145, 3, v144
	s_mov_b32 s44, 0
	v_bfe_u32 v160, v144, 6, 2
	v_mov_b64_e32 v[18:19], v[12:13]
	v_mov_b64_e32 v[16:17], v[10:11]
	v_mov_b64_e32 v[14:15], v[8:9]
	v_mov_b64_e32 v[12:13], v[6:7]
	v_mov_b64_e32 v[10:11], v[4:5]
	v_mov_b64_e32 v[8:9], v[2:3]
	v_mov_b64_e32 v[6:7], v[0:1]
	s_mov_b32 s23, 0
	s_movk_i32 s50, 0xc0
	s_waitcnt vmcnt(0) lgkmcnt(0)
	s_barrier
.LBB0_1076:
	s_add_i32 s35, s44, 0x10000
	s_and_b32 s4, s35, 0x10000
	s_add_i32 s17, s4, 32
	v_add_u32_e32 v2, s17, v163
	v_add_u32_e32 v3, 0x8000, v2
	v_readfirstlane_b32 s4, v2
	v_lshl_add_u64 v[0:1], v[134:135], 0, s[70:71]
	s_mov_b32 m0, s4
	v_readfirstlane_b32 s4, v3
	v_add_u32_e32 v3, 0x2000, v2
	global_load_lds_dwordx4 v[0:1], off nt
	v_lshl_add_u64 v[0:1], v[150:151], 0, s[70:71]
	s_mov_b32 m0, s4
	v_readfirstlane_b32 s4, v3
	v_add_u32_e32 v3, 0xa000, v2
	global_load_lds_dwordx4 v[0:1], off nt
	v_lshl_add_u64 v[0:1], v[136:137], 0, s[70:71]
	s_mov_b32 m0, s4
	v_readfirstlane_b32 s4, v3
	v_add_u32_e32 v3, 0x4000, v2
	global_load_lds_dwordx4 v[0:1], off nt
	v_lshl_add_u64 v[0:1], v[152:153], 0, s[70:71]
	s_mov_b32 m0, s4
	v_readfirstlane_b32 s4, v3
	v_add_u32_e32 v3, 0xc000, v2
	global_load_lds_dwordx4 v[0:1], off nt
	v_lshl_add_u64 v[0:1], v[146:147], 0, s[70:71]
	s_mov_b32 m0, s4
	v_readfirstlane_b32 s4, v3
	v_add_u32_e32 v3, 0x6000, v2
	global_load_lds_dwordx4 v[0:1], off nt
	v_lshl_add_u64 v[0:1], v[154:155], 0, s[70:71]
	s_mov_b32 m0, s4
	v_readfirstlane_b32 s4, v3
	v_add_u32_e32 v2, 0xe000, v2
	global_load_lds_dwordx4 v[0:1], off nt
	v_lshl_add_u64 v[0:1], v[148:149], 0, s[70:71]
	s_mov_b32 m0, s4
	v_readfirstlane_b32 s4, v2
	global_load_lds_dwordx4 v[0:1], off nt
	v_lshl_add_u64 v[0:1], v[156:157], 0, s[70:71]
	s_mov_b32 m0, s4
	s_andn2_b64 vcc, exec, s[74:75]
	global_load_lds_dwordx4 v[0:1], off nt
	v_cndmask_b32_e64 v0, 0, 1, s[74:75]
	v_cmp_ne_u32_e64 s[4:5], 1, v0
	s_mov_b64 s[76:77], s[72:73]
	s_cbranch_vccnz .LBB0_1078
	s_lshr_b32 s45, s23, s18
	v_cmp_eq_u32_e32 vcc, s45, v160
	s_nop 1
	v_cndmask_b32_e64 v0, 0, 1, vcc
	s_nop 0
	v_readfirstlane_b32 s45, v0
	s_bitcmp1_b32 s45, 0
	s_cselect_b64 s[76:77], -1, 0
